# final RMSNorm: each wave normalises 8 consecutive rows of the row panels its own XCD just wrote (L2-local) instead of rows strided by 2048; sample rows as a tail
# baseline (speedup 1.0000x reference)
; #define KP(f) ((decltype(Params::f))karg_ptr<(int)offsetof(Params, f)>())
; __device__ void phase_final() {
;     float* out = KP(out); const float* ssq = KP(ssq); const float* fg = KP(final_g);
;     const int lane = threadIdx.x & 63, gw = blockIdx.x * 8 + (threadIdx.x >> 6), nw = gridDim.x * 8;
;     for (int row = gw; row < T_ALL; row += nw) {
;         const float rs = row_rstd(ssq, row);
;         float* xr = out + (size_t)row * DM;
; #pragma unroll
;         for (int i = 0; i < 4; ++i) { const int c = i * 256 + lane * 4; const f32x4 v = *(const f32x4*)(xr + c); const f32x4 g = *(const f32x4*)(fg + c);
;             *(f32x4*)(xr + c) = v * rs * g; }
;     }
.LBB0_2319:
	s_or_b64 exec, exec, s[6:7]
	s_waitcnt lgkmcnt(0)
	s_barrier
	v_readlane_b32 s8, v230, 4
	s_load_dwordx2 s[2:3], s[0:1], 0xd8
	s_waitcnt lgkmcnt(0)
	s_load_dwordx2 s[4:5], s[0:1], 0x128
	s_waitcnt lgkmcnt(0)
	s_load_dwordx2 s[0:1], s[0:1], 0xd0
	s_waitcnt lgkmcnt(0)
	v_readlane_b32 s9, v230, 5
	s_and_saveexec_b64 s[6:7], s[8:9]
	s_cbranch_execz .LBB0_2322
	v_readfirstlane_b32 s10, v144
	v_bfe_u32 v146, v144, 3, 3
	v_lshrrev_b32_e32 v148, 6, v144
	v_and_b32_e32 v150, 7, v144
	v_lshlrev_b32_e32 v146, 11, v146
	v_lshl_or_b32 v146, v148, 6, v146
	v_lshl_or_b32 v146, v150, 3, v146
	v_mov_b32_e32 v147, 0
	v_add_u32_e32 v152, 0x4000, v144
	v_mov_b32_e32 v153, 0
	v_lshlrev_b64 v[148:149], 6, v[152:153]
	v_lshlrev_b64 v[150:151], 12, v[152:153]
	v_lshlrev_b32_e32 v0, 4, v166
	v_lshlrev_b64 v[2:3], 6, v[146:147]
	v_lshlrev_b64 v[4:5], 12, v[146:147]
	v_and_b32_e32 v0, 0x3f0, v0
	v_mov_b32_e32 v1, 0
	v_lshl_add_u64 v[2:3], s[4:5], 0, v[2:3]
	v_lshl_add_u64 v[148:149], s[4:5], 0, v[148:149]
	s_ashr_i32 s51, s50, 31
	v_lshl_or_b32 v4, v167, 4, v4
	v_lshl_or_b32 v150, v167, 4, v150
	v_lshl_add_u64 v[0:1], s[0:1], 0, v[0:1]
	v_lshl_add_u64 v[2:3], v[2:3], 0, 32
	v_lshl_add_u64 v[148:149], v[148:149], 0, 32
	s_mov_b64 s[0:1], 64
	v_lshl_add_u64 v[4:5], s[2:3], 0, v[4:5]
	v_lshl_add_u64 v[150:151], s[2:3], 0, v[150:151]
	s_mov_b64 s[2:3], 0x1000
	s_mov_b64 s[4:5], 0
	v_mov_b32_e32 v6, 0x358637bd
	s_mov_b32 s6, 0x800000
	s_movk_i32 s7, 0x3fff
	global_load_dwordx4 v[40:43], v[0:1], off
	global_load_dwordx4 v[44:47], v[0:1], off offset:1024
	global_load_dwordx4 v[48:51], v[0:1], off offset:2048
	global_load_dwordx4 v[52:55], v[0:1], off offset:3072
	v_mov_b64_e32 v[92:93], v[4:5]
	global_load_dwordx4 v[8:11], v[2:3], off offset:-32
	global_load_dwordx4 v[12:15], v[2:3], off offset:-16
	global_load_dwordx4 v[16:19], v[2:3], off
	global_load_dwordx4 v[20:23], v[2:3], off offset:16
	global_load_dwordx4 v[24:27], v[4:5], off
	global_load_dwordx4 v[28:31], v[4:5], off offset:1024
	global_load_dwordx4 v[32:35], v[4:5], off offset:2048
	global_load_dwordx4 v[36:39], v[4:5], off offset:3072
	v_add_u32_e32 v144, s50, v144
	v_lshl_add_u64 v[2:3], v[2:3], 0, s[0:1]
	v_lshl_add_u64 v[4:5], v[4:5], 0, s[2:3]
	v_cmp_ge_i32_e32 vcc, s7, v144
	s_cbranch_vccz .Lfin_lastA
	v_mov_b64_e32 v[94:95], v[4:5]
	global_load_dwordx4 v[56:59], v[2:3], off offset:-32
	global_load_dwordx4 v[60:63], v[2:3], off offset:-16
	global_load_dwordx4 v[64:67], v[2:3], off
	global_load_dwordx4 v[68:71], v[2:3], off offset:16
	global_load_dwordx4 v[72:75], v[4:5], off
	global_load_dwordx4 v[76:79], v[4:5], off offset:1024
	global_load_dwordx4 v[80:83], v[4:5], off offset:2048
	global_load_dwordx4 v[84:87], v[4:5], off offset:3072
	s_waitcnt vmcnt(8)
	v_add_f32_e32 v96, v8, v9
	v_add_f32_e32 v97, v10, v11
	v_add_f32_e32 v98, v12, v13
	v_add_f32_e32 v99, v14, v15
	v_add_f32_e32 v100, v16, v17
	v_add_f32_e32 v101, v18, v19
	v_add_f32_e32 v102, v20, v21
	v_add_f32_e32 v103, v22, v23
	v_add_f32_e32 v96, v96, v97
	v_add_f32_e32 v98, v98, v99
	v_add_f32_e32 v100, v100, v101
	v_add_f32_e32 v102, v102, v103
	v_add_f32_e32 v96, v96, v98
	v_add_f32_e32 v96, v96, v100
	v_add_f32_e32 v96, v96, v102
	v_fmamk_f32 v96, v96, 0x3a800000, v6
	v_mul_f32_e32 v97, 0x4b800000, v96
	v_cmp_gt_f32_e32 vcc, s6, v96
	s_nop 1
	v_cndmask_b32_e32 v96, v96, v97, vcc
	v_rsq_f32_e32 v96, v96
	s_nop 0
	v_mul_f32_e32 v97, 0x45800000, v96
	v_cndmask_b32_e32 v90, v96, v97, vcc
	v_pk_mul_f32 v[24:25], v[24:25], v[90:91] op_sel_hi:[1,0]
	v_pk_mul_f32 v[26:27], v[26:27], v[90:91] op_sel_hi:[1,0]
	v_pk_mul_f32 v[24:25], v[40:41], v[24:25]
	v_pk_mul_f32 v[26:27], v[42:43], v[26:27]
	global_store_dwordx4 v[92:93], v[24:27], off
	v_pk_mul_f32 v[28:29], v[28:29], v[90:91] op_sel_hi:[1,0]
	v_pk_mul_f32 v[30:31], v[30:31], v[90:91] op_sel_hi:[1,0]
	v_pk_mul_f32 v[28:29], v[44:45], v[28:29]
	v_pk_mul_f32 v[30:31], v[46:47], v[30:31]
	global_store_dwordx4 v[92:93], v[28:31], off offset:1024
	v_pk_mul_f32 v[32:33], v[32:33], v[90:91] op_sel_hi:[1,0]
	v_pk_mul_f32 v[34:35], v[34:35], v[90:91] op_sel_hi:[1,0]
	v_pk_mul_f32 v[32:33], v[48:49], v[32:33]
	v_pk_mul_f32 v[34:35], v[50:51], v[34:35]
	global_store_dwordx4 v[92:93], v[32:35], off offset:2048
	v_pk_mul_f32 v[36:37], v[36:37], v[90:91] op_sel_hi:[1,0]
	v_pk_mul_f32 v[38:39], v[38:39], v[90:91] op_sel_hi:[1,0]
	v_pk_mul_f32 v[36:37], v[52:53], v[36:37]
	v_pk_mul_f32 v[38:39], v[54:55], v[38:39]
	global_store_dwordx4 v[92:93], v[36:39], off offset:3072

; __device__ __forceinline__ float row_rstd(const float* ssq, int row) {
;     const f32x4* p = (const f32x4*)(ssq + (size_t)row * 16);
;     const f32x4 a = p[0], b = p[1], c = p[2], d = p[3];
;     const float s = ((a[0] + a[1]) + (a[2] + a[3])) + ((b[0] + b[1]) + (b[2] + b[3])) + ((c[0] + c[1]) + (c[2] + c[3])) + ((d[0] + d[1]) + (d[2] + d[3]));
;     return rsqrtf(s * (1.0f / 1024.0f) + 1e-6f);
; __device__ void phase_final() {
;     ...
;         const float rs = row_rstd(ssq, row);
;         float* xr = out + (size_t)row * DM;
; #pragma unroll
;         for (int i = 0; i < 4; ++i) { const int c = i * 256 + lane * 4; const f32x4 v = *(const f32x4*)(xr + c); const f32x4 g = *(const f32x4*)(fg + c);
;             *(f32x4*)(xr + c) = v * rs * g; }
.Lfin_tail:
	s_cmpk_lt_u32 s10, 0x400
	s_cbranch_scc0 .Lfin_done
	v_mov_b64_e32 v[2:3], v[148:149]
	v_mov_b64_e32 v[4:5], v[150:151]
	v_mov_b64_e32 v[92:93], v[4:5]
	global_load_dwordx4 v[8:11], v[2:3], off offset:-32
	global_load_dwordx4 v[12:15], v[2:3], off offset:-16
	global_load_dwordx4 v[16:19], v[2:3], off
	global_load_dwordx4 v[20:23], v[2:3], off offset:16
	global_load_dwordx4 v[24:27], v[4:5], off
	global_load_dwordx4 v[28:31], v[4:5], off offset:1024
	global_load_dwordx4 v[32:35], v[4:5], off offset:2048
	global_load_dwordx4 v[36:39], v[4:5], off offset:3072
	s_waitcnt vmcnt(0)
	v_add_f32_e32 v96, v8, v9
	v_add_f32_e32 v97, v10, v11
	v_add_f32_e32 v98, v12, v13
	v_add_f32_e32 v99, v14, v15
	v_add_f32_e32 v100, v16, v17
	v_add_f32_e32 v101, v18, v19
	v_add_f32_e32 v102, v20, v21
	v_add_f32_e32 v103, v22, v23
	v_add_f32_e32 v96, v96, v97
	v_add_f32_e32 v98, v98, v99
	v_add_f32_e32 v100, v100, v101
	v_add_f32_e32 v102, v102, v103
	v_add_f32_e32 v96, v96, v98
	v_add_f32_e32 v96, v96, v100
	v_add_f32_e32 v96, v96, v102
	v_fmamk_f32 v96, v96, 0x3a800000, v6
	v_mul_f32_e32 v97, 0x4b800000, v96
	v_cmp_gt_f32_e32 vcc, s6, v96
	s_nop 1
	v_cndmask_b32_e32 v96, v96, v97, vcc
	v_rsq_f32_e32 v96, v96
	s_nop 0
	v_mul_f32_e32 v97, 0x45800000, v96
	v_cndmask_b32_e32 v90, v96, v97, vcc
	v_pk_mul_f32 v[24:25], v[24:25], v[90:91] op_sel_hi:[1,0]
	v_pk_mul_f32 v[26:27], v[26:27], v[90:91] op_sel_hi:[1,0]
	v_pk_mul_f32 v[24:25], v[40:41], v[24:25]
	v_pk_mul_f32 v[26:27], v[42:43], v[26:27]
	global_store_dwordx4 v[92:93], v[24:27], off
	v_pk_mul_f32 v[28:29], v[28:29], v[90:91] op_sel_hi:[1,0]
	v_pk_mul_f32 v[30:31], v[30:31], v[90:91] op_sel_hi:[1,0]
	v_pk_mul_f32 v[28:29], v[44:45], v[28:29]
	v_pk_mul_f32 v[30:31], v[46:47], v[30:31]
	global_store_dwordx4 v[92:93], v[28:31], off offset:1024
	v_pk_mul_f32 v[32:33], v[32:33], v[90:91] op_sel_hi:[1,0]
	v_pk_mul_f32 v[34:35], v[34:35], v[90:91] op_sel_hi:[1,0]
	v_pk_mul_f32 v[32:33], v[48:49], v[32:33]
	v_pk_mul_f32 v[34:35], v[50:51], v[34:35]
	global_store_dwordx4 v[92:93], v[32:35], off offset:2048
	v_pk_mul_f32 v[36:37], v[36:37], v[90:91] op_sel_hi:[1,0]
	v_pk_mul_f32 v[38:39], v[38:39], v[90:91] op_sel_hi:[1,0]
	v_pk_mul_f32 v[36:37], v[52:53], v[36:37]
	v_pk_mul_f32 v[38:39], v[54:55], v[38:39]
	global_store_dwordx4 v[92:93], v[36:39], off offset:3072
.Lfin_done:
.LBB0_2322:
	s_endpgm
